# phase 8 (ik layernorm+rope): ds_bpermute butterflies replaced by DPP/permlane-swap VALU reductions, next-row loads prefetched
# baseline (speedup 1.0000x reference)
; DI bf16_t to_bf16(float a) { return (bf16_t)(pk_bf16(a, 0.f) & 0xffffu); }
; DI void phase_iknorm(const Params& p) {
;     ...
;     for (int row = blockIdx.x * 8 + wid; row < T_TOK; row += gridDim.x * 8) {
;         const float x = ikraw[(size_t)row * 64 + lane];
;         const float mean = wave_sum(x) * (1.0f / 64.0f);
;         const float d = x - mean;
;         const float var = wave_sum(d * d) * (1.0f / 64.0f);
;         float y = d * rsqrtf(var + EPS) * g + bt;
;         const int s = row & (SEQ - 1);
;         const float other = __shfl_xor(y, 8);
;         const float cs = rope[s * 16 + (lane & 7)], sn = rope[s * 16 + 8 + (lane & 7)];
;         if (lane < 8) y = y * cs - other * sn; else if (lane < 16) y = y * cs + other * sn;
;         ikb[(size_t)row * 64 + lane] = to_bf16(y);
;     }
.LBB0_2541:
	s_or_b64 exec, exec, s[2:3]
	v_cmp_gt_i32_e32 vcc, 9, v1
	v_cmp_lt_i32_e64 s[2:3], 8, v5
	s_and_b64 s[0:1], vcc, s[2:3]
	v_bfe_u32 v6, v0, 6, 4
	s_waitcnt lgkmcnt(0)
	s_and_saveexec_b64 s[8:9], s[0:1]
	s_cbranch_execz .LBB0_2545
	v_lshl_or_b32 v2, s33, 3, v6
	s_mov_b32 s0, 0x8000
	v_cmp_gt_i32_e64 s[2:3], s0, v2
	s_and_b64 exec, exec, s[2:3]
	s_cbranch_execz .LBB0_2545
	s_load_dwordx4 s[0:3], s[88:89], 0x58
	v_and_b32_e32 v3, 0x3ff, v0
	v_and_b32_e32 v4, 63, v3
	v_lshlrev_b32_e32 v9, 2, v4
	s_add_u32 s10, s42, 0x1d200000
	s_waitcnt lgkmcnt(0)
	global_load_dword v7, v9, s[2:3]
	global_load_dword v8, v9, s[0:1]
	s_addc_u32 s11, s43, 0
	s_add_u32 s12, s42, 0x1f200000
	s_addc_u32 s13, s43, 0
	s_add_u32 s14, s42, 0x1f9a0000
	s_addc_u32 s15, s43, 0
	v_and_b32_e32 v15, 7, v3
	v_lshlrev_b32_e32 v3, 4, v6
	v_cmp_gt_u32_e64 s[2:3], 8, v4
	v_cmp_gt_u32_e64 s[4:5], 16, v4
	s_lshl_b32 s0, s86, 3
	v_lshl_add_u32 v16, s33, 7, v3
	s_lshl_b32 s1, s86, 7
	s_mov_b64 s[16:17], 0
	v_mov_b32_e32 v17, 0x358637bd
	s_mov_b32 s18, 0x800000
	s_mov_b32 s19, 0x1fff0
	s_movk_i32 s20, 0x7fff
	v_lshl_or_b32 v13, v2, 6, v4
	v_lshlrev_b32_e32 v14, 2, v13
	global_load_dword v9, v14, s[10:11]
	v_and_or_b32 v14, v16, s19, v15
	v_lshlrev_b32_e32 v14, 2, v14
	global_load_dword v10, v14, s[14:15]
	global_load_dword v11, v14, s[14:15] offset:32
	v_lshlrev_b32_e32 v12, 1, v13
	s_waitcnt vmcnt(0)
.LBB0_2544:
	v_mov_b32_e32 v3, v9
	v_mov_b32_e32 v20, v10
	v_mov_b32_e32 v21, v11
	v_mov_b32_e32 v18, v12
	v_add_u32_e32 v2, s0, v2
	v_add_u32_e32 v16, s1, v16
	v_min_i32_e32 v13, s20, v2
	v_lshl_or_b32 v13, v13, 6, v4
	v_lshlrev_b32_e32 v14, 2, v13
	global_load_dword v9, v14, s[10:11]
	v_and_or_b32 v14, v16, s19, v15
	v_lshlrev_b32_e32 v14, 2, v14
	global_load_dword v10, v14, s[14:15]
	global_load_dword v11, v14, s[14:15] offset:32
	v_lshlrev_b32_e32 v12, 1, v13
	v_mov_b32_e32 v22, v3
	v_mov_b32_e32 v23, v22
	s_nop 1
	v_permlane32_swap_b32_e32 v22, v23
	v_add_f32_e32 v22, v22, v23
	v_mov_b32_e32 v23, v22
	s_nop 1
	v_permlane16_swap_b32_e32 v22, v23
	v_add_f32_e32 v22, v22, v23
	s_nop 1
	v_add_f32_dpp v22, v22, v22 row_ror:8 row_mask:0xf bank_mask:0xf
	s_nop 1
	v_add_f32_dpp v22, v22, v22 row_ror:4 row_mask:0xf bank_mask:0xf
	s_nop 1
	v_add_f32_dpp v22, v22, v22 quad_perm:[2,3,0,1] row_mask:0xf bank_mask:0xf
	s_nop 1
	v_add_f32_dpp v22, v22, v22 quad_perm:[1,0,3,2] row_mask:0xf bank_mask:0xf
	v_fmac_f32_e32 v3, 0xbc800000, v22
	v_mul_f32_e32 v22, v3, v3
	v_mov_b32_e32 v23, v22
	s_nop 1
	v_permlane32_swap_b32_e32 v22, v23
	v_add_f32_e32 v22, v22, v23
	v_mov_b32_e32 v23, v22
	s_nop 1
	v_permlane16_swap_b32_e32 v22, v23
	v_add_f32_e32 v22, v22, v23
	s_nop 1
	v_add_f32_dpp v22, v22, v22 row_ror:8 row_mask:0xf bank_mask:0xf
	s_nop 1
	v_add_f32_dpp v22, v22, v22 row_ror:4 row_mask:0xf bank_mask:0xf
	s_nop 1
	v_add_f32_dpp v22, v22, v22 quad_perm:[2,3,0,1] row_mask:0xf bank_mask:0xf
	s_nop 1
	v_add_f32_dpp v22, v22, v22 quad_perm:[1,0,3,2] row_mask:0xf bank_mask:0xf
	v_fmamk_f32 v22, v22, 0x3c800000, v17
	v_mul_f32_e32 v23, 0x4b800000, v22
	v_cmp_gt_f32_e64 s[6:7], s18, v22
	s_nop 1
	v_cndmask_b32_e64 v22, v22, v23, s[6:7]
	v_rsq_f32_e32 v22, v22
	s_nop 0
	v_mul_f32_e32 v23, 0x45800000, v22
	v_cndmask_b32_e64 v22, v22, v23, s[6:7]
	v_mul_f32_e32 v3, v3, v22
	v_fma_f32 v22, v8, v3, v7
	s_nop 1
	v_mov_b32_dpp v23, v22 row_ror:8 row_mask:0xf bank_mask:0xf
	v_cmp_lt_i32_e64 s[6:7], s20, v2
	s_or_b64 s[16:17], s[6:7], s[16:17]
	v_pk_mul_f32 v[20:21], v[20:21], v[22:23]
	s_nop 0
	v_sub_f32_e32 v3, v20, v21
	v_add_f32_e32 v20, v21, v20
	v_cndmask_b32_e64 v20, v22, v20, s[4:5]
	v_cndmask_b32_e64 v3, v20, v3, s[2:3]
	v_cvt_pk_bf16_f32 v3, v3, s0
	global_store_short v18, v3, s[12:13]
	s_waitcnt vmcnt(1)
	s_andn2_b64 exec, exec, s[16:17]
	s_cbranch_execnz .LBB0_2544
